# S6 H-output stores marked non-temporal (nt) so dirty lines leave L2 early
# baseline (speedup 1.0000x reference)
; __device__ __forceinline__ unsigned cvt_pk_bf16(float lo, float hi) { unsigned r; asm volatile("v_cvt_pk_bf16_f32 %0, %1, %2" : "=v"(r) : "v"(lo), "v"(hi)); return r; }
; __device__ __forceinline__ float swiglu1(float g, float u) { return g * u * __builtin_amdgcn_rcpf(1.0f + __expf(-g)); }
;     __device__ __forceinline__ void operator()(const f32x4 (&acc)[2][2][4][2], const Unit& u, int wr, int wc, int fr, int fq) const {
;         const int row0 = u.pm * BM + wr * 64 + fr, col0 = u.pn * HALF + wc * 32 + 8 * fq;
; #pragma unroll
;         for (int ai = 0; ai < 2; ++ai)
; #pragma unroll
;             for (int m = 0; m < 4; ++m) { bf16_t* rowp = O + (size_t)(row0 + ai * HALF + m * 16) * ldc + col0;
;                 const f32x4 g0 = acc[ai][0][m][0], g1 = acc[ai][0][m][1], u0 = acc[ai][1][m][0], u1 = acc[ai][1][m][1];
;                 u32x4 w; w.x = cvt_pk_bf16(swiglu1(g0[0], u0[0]), swiglu1(g0[1], u0[1])); w.y = cvt_pk_bf16(swiglu1(g0[2], u0[2]), swiglu1(g0[3], u0[3]));
;                 w.z = cvt_pk_bf16(swiglu1(g1[0], u1[0]), swiglu1(g1[1], u1[1])); w.w = cvt_pk_bf16(swiglu1(g1[2], u1[2]), swiglu1(g1[3], u1[3]));
;                 *(u32x4*)rowp = w; }
.LBB0_969:
	s_mov_b32 s48, 0xbfb8aa3b
	s_mov_b32 s50, 1.0
	v_readlane_b32 s14, v254, 6
	v_lshl_or_b32 v142, s30, 7, v146
	v_readlane_b32 s15, v254, 7
	v_lshl_add_u32 v148, s31, 8, v144
	v_ashrrev_i32_e32 v143, 31, v142
	v_mov_b64_e32 v[140:141], s[14:15]
	s_movk_i32 s7, 0x2c00
	v_lshlrev_b64 v[142:143], 1, v[142:143]
	v_pk_mul_f32 v[122:123], v[126:127], v[122:123]
	v_pk_mul_f32 v[124:125], v[128:129], v[124:125]
	v_pk_mul_f32 v[114:115], v[118:119], v[114:115]
	v_pk_mul_f32 v[116:117], v[120:121], v[116:117]
	v_pk_mul_f32 v[126:127], v[126:127], s[48:49] op_sel_hi:[1,0]
	v_pk_mul_f32 v[128:129], v[128:129], s[48:49] op_sel_hi:[1,0]
	v_pk_mul_f32 v[118:119], v[118:119], s[48:49] op_sel_hi:[1,0]
	v_pk_mul_f32 v[120:121], v[120:121], s[48:49] op_sel_hi:[1,0]
	v_exp_f32_e32 v126, v126
	v_exp_f32_e32 v127, v127
	v_exp_f32_e32 v128, v128
	v_exp_f32_e32 v129, v129
	v_exp_f32_e32 v118, v118
	v_exp_f32_e32 v119, v119
	v_exp_f32_e32 v120, v120
	v_exp_f32_e32 v121, v121
	v_pk_add_f32 v[126:127], v[126:127], s[50:51] op_sel_hi:[1,0]
	v_pk_add_f32 v[128:129], v[128:129], s[50:51] op_sel_hi:[1,0]
	v_pk_add_f32 v[118:119], v[118:119], s[50:51] op_sel_hi:[1,0]
	v_pk_add_f32 v[120:121], v[120:121], s[50:51] op_sel_hi:[1,0]
	v_rcp_f32_e32 v126, v126
	v_rcp_f32_e32 v127, v127
	v_rcp_f32_e32 v128, v128
	v_rcp_f32_e32 v129, v129
	v_rcp_f32_e32 v118, v118
	v_rcp_f32_e32 v119, v119
	v_rcp_f32_e32 v120, v120
	v_rcp_f32_e32 v121, v121
	v_pk_mul_f32 v[106:107], v[110:111], v[106:107]
	v_pk_mul_f32 v[108:109], v[112:113], v[108:109]
	v_pk_mul_f32 v[98:99], v[102:103], v[98:99]
	v_pk_mul_f32 v[100:101], v[104:105], v[100:101]
	v_pk_mul_f32 v[110:111], v[110:111], s[48:49] op_sel_hi:[1,0]
	v_pk_mul_f32 v[112:113], v[112:113], s[48:49] op_sel_hi:[1,0]
	v_pk_mul_f32 v[102:103], v[102:103], s[48:49] op_sel_hi:[1,0]
	v_pk_mul_f32 v[104:105], v[104:105], s[48:49] op_sel_hi:[1,0]
	v_pk_mul_f32 v[122:123], v[126:127], v[122:123]
	v_pk_mul_f32 v[124:125], v[128:129], v[124:125]
	v_pk_mul_f32 v[114:115], v[118:119], v[114:115]
	v_pk_mul_f32 v[116:117], v[120:121], v[116:117]
	v_cvt_pk_bf16_f32 v122, v122, v123
	v_cvt_pk_bf16_f32 v123, v124, v125
	v_cvt_pk_bf16_f32 v124, v114, v115
	v_cvt_pk_bf16_f32 v125, v116, v117
	v_mov_b32_e32 v126, v148
	v_mad_i64_i32 v[126:127], s[14:15], v126, s7, v[140:141]
	v_lshl_add_u64 v[126:127], v[126:127], 0, v[142:143]
	global_store_dwordx4 v[126:127], v[122:125], off nt
	v_exp_f32_e32 v110, v110
	v_exp_f32_e32 v111, v111
	v_exp_f32_e32 v112, v112
	v_exp_f32_e32 v113, v113
	v_exp_f32_e32 v102, v102
	v_exp_f32_e32 v103, v103
	v_exp_f32_e32 v104, v104
	v_exp_f32_e32 v105, v105
	v_pk_add_f32 v[110:111], v[110:111], s[50:51] op_sel_hi:[1,0]
	v_pk_add_f32 v[112:113], v[112:113], s[50:51] op_sel_hi:[1,0]
	v_pk_add_f32 v[102:103], v[102:103], s[50:51] op_sel_hi:[1,0]
	v_pk_add_f32 v[104:105], v[104:105], s[50:51] op_sel_hi:[1,0]
	v_rcp_f32_e32 v110, v110
	v_rcp_f32_e32 v111, v111
	v_rcp_f32_e32 v112, v112
	v_rcp_f32_e32 v113, v113
	v_rcp_f32_e32 v102, v102
	v_rcp_f32_e32 v103, v103
	v_rcp_f32_e32 v104, v104
	v_rcp_f32_e32 v105, v105
	v_pk_mul_f32 v[90:91], v[94:95], v[90:91]
	v_pk_mul_f32 v[92:93], v[96:97], v[92:93]
	v_pk_mul_f32 v[82:83], v[86:87], v[82:83]
	v_pk_mul_f32 v[84:85], v[88:89], v[84:85]
	v_pk_mul_f32 v[94:95], v[94:95], s[48:49] op_sel_hi:[1,0]
	v_pk_mul_f32 v[96:97], v[96:97], s[48:49] op_sel_hi:[1,0]
	v_pk_mul_f32 v[86:87], v[86:87], s[48:49] op_sel_hi:[1,0]
	v_pk_mul_f32 v[88:89], v[88:89], s[48:49] op_sel_hi:[1,0]
	v_pk_mul_f32 v[106:107], v[110:111], v[106:107]
	v_pk_mul_f32 v[108:109], v[112:113], v[108:109]
	v_pk_mul_f32 v[98:99], v[102:103], v[98:99]
	v_pk_mul_f32 v[100:101], v[104:105], v[100:101]
	v_cvt_pk_bf16_f32 v106, v106, v107
	v_cvt_pk_bf16_f32 v107, v108, v109
	v_cvt_pk_bf16_f32 v108, v98, v99
	v_cvt_pk_bf16_f32 v109, v100, v101
	v_or_b32_e32 v110, 16, v148
	v_mad_i64_i32 v[110:111], s[14:15], v110, s7, v[140:141]
	v_lshl_add_u64 v[110:111], v[110:111], 0, v[142:143]
	global_store_dwordx4 v[110:111], v[106:109], off nt
	v_exp_f32_e32 v94, v94
	v_exp_f32_e32 v95, v95
	v_exp_f32_e32 v96, v96
	v_exp_f32_e32 v97, v97
	v_exp_f32_e32 v86, v86
	v_exp_f32_e32 v87, v87
	v_exp_f32_e32 v88, v88
	v_exp_f32_e32 v89, v89
	v_pk_add_f32 v[94:95], v[94:95], s[50:51] op_sel_hi:[1,0]
	v_pk_add_f32 v[96:97], v[96:97], s[50:51] op_sel_hi:[1,0]
	v_pk_add_f32 v[86:87], v[86:87], s[50:51] op_sel_hi:[1,0]
	v_pk_add_f32 v[88:89], v[88:89], s[50:51] op_sel_hi:[1,0]
	v_rcp_f32_e32 v94, v94
	v_rcp_f32_e32 v95, v95
	v_rcp_f32_e32 v96, v96
	v_rcp_f32_e32 v97, v97
	v_rcp_f32_e32 v86, v86
	v_rcp_f32_e32 v87, v87
	v_rcp_f32_e32 v88, v88
	v_rcp_f32_e32 v89, v89
	v_pk_mul_f32 v[74:75], v[78:79], v[74:75]
	v_pk_mul_f32 v[76:77], v[80:81], v[76:77]
	v_pk_mul_f32 v[66:67], v[70:71], v[66:67]
	v_pk_mul_f32 v[68:69], v[72:73], v[68:69]
	v_pk_mul_f32 v[78:79], v[78:79], s[48:49] op_sel_hi:[1,0]
	v_pk_mul_f32 v[80:81], v[80:81], s[48:49] op_sel_hi:[1,0]
	v_pk_mul_f32 v[70:71], v[70:71], s[48:49] op_sel_hi:[1,0]
	v_pk_mul_f32 v[72:73], v[72:73], s[48:49] op_sel_hi:[1,0]
	v_pk_mul_f32 v[90:91], v[94:95], v[90:91]
	v_pk_mul_f32 v[92:93], v[96:97], v[92:93]
	v_pk_mul_f32 v[82:83], v[86:87], v[82:83]
	v_pk_mul_f32 v[84:85], v[88:89], v[84:85]
	v_cvt_pk_bf16_f32 v90, v90, v91
	v_cvt_pk_bf16_f32 v91, v92, v93
	v_cvt_pk_bf16_f32 v92, v82, v83
	v_cvt_pk_bf16_f32 v93, v84, v85
	v_or_b32_e32 v94, 32, v148
	v_mad_i64_i32 v[94:95], s[14:15], v94, s7, v[140:141]
	v_lshl_add_u64 v[94:95], v[94:95], 0, v[142:143]
	global_store_dwordx4 v[94:95], v[90:93], off nt
	v_exp_f32_e32 v78, v78
	v_exp_f32_e32 v79, v79
	v_exp_f32_e32 v80, v80
	v_exp_f32_e32 v81, v81
	v_exp_f32_e32 v70, v70
; __device__ __forceinline__ unsigned cvt_pk_bf16(float lo, float hi) { unsigned r; asm volatile("v_cvt_pk_bf16_f32 %0, %1, %2" : "=v"(r) : "v"(lo), "v"(hi)); return r; }
; __device__ __forceinline__ float swiglu1(float g, float u) { return g * u * __builtin_amdgcn_rcpf(1.0f + __expf(-g)); }
;     __device__ __forceinline__ void operator()(const f32x4 (&acc)[2][2][4][2], const Unit& u, int wr, int wc, int fr, int fq) const {
;         const int row0 = u.pm * BM + wr * 64 + fr, col0 = u.pn * HALF + wc * 32 + 8 * fq;
; #pragma unroll
;         for (int ai = 0; ai < 2; ++ai)
; #pragma unroll
;             for (int m = 0; m < 4; ++m) { bf16_t* rowp = O + (size_t)(row0 + ai * HALF + m * 16) * ldc + col0;
;                 const f32x4 g0 = acc[ai][0][m][0], g1 = acc[ai][0][m][1], u0 = acc[ai][1][m][0], u1 = acc[ai][1][m][1];
;                 u32x4 w; w.x = cvt_pk_bf16(swiglu1(g0[0], u0[0]), swiglu1(g0[1], u0[1])); w.y = cvt_pk_bf16(swiglu1(g0[2], u0[2]), swiglu1(g0[3], u0[3]));
;                 w.z = cvt_pk_bf16(swiglu1(g1[0], u1[0]), swiglu1(g1[1], u1[1])); w.w = cvt_pk_bf16(swiglu1(g1[2], u1[2]), swiglu1(g1[3], u1[3]));
;                 *(u32x4*)rowp = w; }
	v_exp_f32_e32 v71, v71
	v_exp_f32_e32 v72, v72
	v_exp_f32_e32 v73, v73
	v_pk_add_f32 v[78:79], v[78:79], s[50:51] op_sel_hi:[1,0]
	v_pk_add_f32 v[80:81], v[80:81], s[50:51] op_sel_hi:[1,0]
	v_pk_add_f32 v[70:71], v[70:71], s[50:51] op_sel_hi:[1,0]
	v_pk_add_f32 v[72:73], v[72:73], s[50:51] op_sel_hi:[1,0]
	v_rcp_f32_e32 v78, v78
	v_rcp_f32_e32 v79, v79
	v_rcp_f32_e32 v80, v80
	v_rcp_f32_e32 v81, v81
	v_rcp_f32_e32 v70, v70
	v_rcp_f32_e32 v71, v71
	v_rcp_f32_e32 v72, v72
	v_rcp_f32_e32 v73, v73
	v_pk_mul_f32 v[58:59], v[62:63], v[58:59]
	v_pk_mul_f32 v[60:61], v[64:65], v[60:61]
	v_pk_mul_f32 v[50:51], v[54:55], v[50:51]
	v_pk_mul_f32 v[52:53], v[56:57], v[52:53]
	v_pk_mul_f32 v[62:63], v[62:63], s[48:49] op_sel_hi:[1,0]
	v_pk_mul_f32 v[64:65], v[64:65], s[48:49] op_sel_hi:[1,0]
	v_pk_mul_f32 v[54:55], v[54:55], s[48:49] op_sel_hi:[1,0]
	v_pk_mul_f32 v[56:57], v[56:57], s[48:49] op_sel_hi:[1,0]
	v_pk_mul_f32 v[74:75], v[78:79], v[74:75]
	v_pk_mul_f32 v[76:77], v[80:81], v[76:77]
	v_pk_mul_f32 v[66:67], v[70:71], v[66:67]
	v_pk_mul_f32 v[68:69], v[72:73], v[68:69]
	v_cvt_pk_bf16_f32 v74, v74, v75
	v_cvt_pk_bf16_f32 v75, v76, v77
	v_cvt_pk_bf16_f32 v76, v66, v67
	v_cvt_pk_bf16_f32 v77, v68, v69
	v_or_b32_e32 v78, 48, v148
	v_mad_i64_i32 v[78:79], s[14:15], v78, s7, v[140:141]
	v_lshl_add_u64 v[78:79], v[78:79], 0, v[142:143]
	global_store_dwordx4 v[78:79], v[74:77], off nt
	v_exp_f32_e32 v62, v62
	v_exp_f32_e32 v63, v63
	v_exp_f32_e32 v64, v64
	v_exp_f32_e32 v65, v65
	v_exp_f32_e32 v54, v54
	v_exp_f32_e32 v55, v55
	v_exp_f32_e32 v56, v56
	v_exp_f32_e32 v57, v57
	v_pk_add_f32 v[62:63], v[62:63], s[50:51] op_sel_hi:[1,0]
	v_pk_add_f32 v[64:65], v[64:65], s[50:51] op_sel_hi:[1,0]
	v_pk_add_f32 v[54:55], v[54:55], s[50:51] op_sel_hi:[1,0]
	v_pk_add_f32 v[56:57], v[56:57], s[50:51] op_sel_hi:[1,0]
	v_rcp_f32_e32 v62, v62
	v_rcp_f32_e32 v63, v63
	v_rcp_f32_e32 v64, v64
	v_rcp_f32_e32 v65, v65
	v_rcp_f32_e32 v54, v54
	v_rcp_f32_e32 v55, v55
	v_rcp_f32_e32 v56, v56
	v_rcp_f32_e32 v57, v57
	v_pk_mul_f32 v[42:43], v[46:47], v[42:43]
	v_pk_mul_f32 v[44:45], v[48:49], v[44:45]
	v_pk_mul_f32 v[34:35], v[38:39], v[34:35]
	v_pk_mul_f32 v[36:37], v[40:41], v[36:37]
	v_pk_mul_f32 v[46:47], v[46:47], s[48:49] op_sel_hi:[1,0]
	v_pk_mul_f32 v[48:49], v[48:49], s[48:49] op_sel_hi:[1,0]
	v_pk_mul_f32 v[38:39], v[38:39], s[48:49] op_sel_hi:[1,0]
	v_pk_mul_f32 v[40:41], v[40:41], s[48:49] op_sel_hi:[1,0]
	v_pk_mul_f32 v[58:59], v[62:63], v[58:59]
	v_pk_mul_f32 v[60:61], v[64:65], v[60:61]
	v_pk_mul_f32 v[50:51], v[54:55], v[50:51]
	v_pk_mul_f32 v[52:53], v[56:57], v[52:53]
	v_cvt_pk_bf16_f32 v58, v58, v59
	v_cvt_pk_bf16_f32 v59, v60, v61
	v_cvt_pk_bf16_f32 v60, v50, v51
	v_cvt_pk_bf16_f32 v61, v52, v53
	v_add_u32_e32 v62, 0x80, v148
	v_mad_i64_i32 v[62:63], s[14:15], v62, s7, v[140:141]
	v_lshl_add_u64 v[62:63], v[62:63], 0, v[142:143]
	global_store_dwordx4 v[62:63], v[58:61], off nt
	v_exp_f32_e32 v46, v46
	v_exp_f32_e32 v47, v47
	v_exp_f32_e32 v48, v48
	v_exp_f32_e32 v49, v49
	v_exp_f32_e32 v38, v38
	v_exp_f32_e32 v39, v39
	v_exp_f32_e32 v40, v40
	v_exp_f32_e32 v41, v41
	v_pk_add_f32 v[46:47], v[46:47], s[50:51] op_sel_hi:[1,0]
	v_pk_add_f32 v[48:49], v[48:49], s[50:51] op_sel_hi:[1,0]
	v_pk_add_f32 v[38:39], v[38:39], s[50:51] op_sel_hi:[1,0]
	v_pk_add_f32 v[40:41], v[40:41], s[50:51] op_sel_hi:[1,0]
	v_rcp_f32_e32 v46, v46
	v_rcp_f32_e32 v47, v47
	v_rcp_f32_e32 v48, v48
	v_rcp_f32_e32 v49, v49
	v_rcp_f32_e32 v38, v38
	v_rcp_f32_e32 v39, v39
	v_rcp_f32_e32 v40, v40
	v_rcp_f32_e32 v41, v41
	v_pk_mul_f32 v[26:27], v[30:31], v[26:27]
; __device__ __forceinline__ unsigned cvt_pk_bf16(float lo, float hi) { unsigned r; asm volatile("v_cvt_pk_bf16_f32 %0, %1, %2" : "=v"(r) : "v"(lo), "v"(hi)); return r; }
; __device__ __forceinline__ float swiglu1(float g, float u) { return g * u * __builtin_amdgcn_rcpf(1.0f + __expf(-g)); }
;     __device__ __forceinline__ void operator()(const f32x4 (&acc)[2][2][4][2], const Unit& u, int wr, int wc, int fr, int fq) const {
;         const int row0 = u.pm * BM + wr * 64 + fr, col0 = u.pn * HALF + wc * 32 + 8 * fq;
; #pragma unroll
;         for (int ai = 0; ai < 2; ++ai)
; #pragma unroll
;             for (int m = 0; m < 4; ++m) { bf16_t* rowp = O + (size_t)(row0 + ai * HALF + m * 16) * ldc + col0;
;                 const f32x4 g0 = acc[ai][0][m][0], g1 = acc[ai][0][m][1], u0 = acc[ai][1][m][0], u1 = acc[ai][1][m][1];
;                 u32x4 w; w.x = cvt_pk_bf16(swiglu1(g0[0], u0[0]), swiglu1(g0[1], u0[1])); w.y = cvt_pk_bf16(swiglu1(g0[2], u0[2]), swiglu1(g0[3], u0[3]));
;                 w.z = cvt_pk_bf16(swiglu1(g1[0], u1[0]), swiglu1(g1[1], u1[1])); w.w = cvt_pk_bf16(swiglu1(g1[2], u1[2]), swiglu1(g1[3], u1[3]));
;                 *(u32x4*)rowp = w; }
; template <class Epi, class Sched, bool ALIGN_EPI = false, bool SP2 = false>
; __device__ __forceinline__ void gemm_phase(PG8_LAS unsigned char* lds, const Gemm g, const Sched& S, const Epi& E) {
;     ...
;         if (!has_next) break;
	v_pk_mul_f32 v[28:29], v[32:33], v[28:29]
	v_pk_mul_f32 v[18:19], v[22:23], v[18:19]
	v_pk_mul_f32 v[20:21], v[24:25], v[20:21]
	v_pk_mul_f32 v[30:31], v[30:31], s[48:49] op_sel_hi:[1,0]
	v_pk_mul_f32 v[32:33], v[32:33], s[48:49] op_sel_hi:[1,0]
	v_pk_mul_f32 v[22:23], v[22:23], s[48:49] op_sel_hi:[1,0]
	v_pk_mul_f32 v[24:25], v[24:25], s[48:49] op_sel_hi:[1,0]
	v_pk_mul_f32 v[42:43], v[46:47], v[42:43]
	v_pk_mul_f32 v[44:45], v[48:49], v[44:45]
	v_pk_mul_f32 v[34:35], v[38:39], v[34:35]
	v_pk_mul_f32 v[36:37], v[40:41], v[36:37]
	v_cvt_pk_bf16_f32 v42, v42, v43
	v_cvt_pk_bf16_f32 v43, v44, v45
	v_cvt_pk_bf16_f32 v44, v34, v35
	v_cvt_pk_bf16_f32 v45, v36, v37
	v_add_u32_e32 v46, 0x90, v148
	v_mad_i64_i32 v[46:47], s[14:15], v46, s7, v[140:141]
	v_lshl_add_u64 v[46:47], v[46:47], 0, v[142:143]
	global_store_dwordx4 v[46:47], v[42:45], off nt
	v_exp_f32_e32 v30, v30
	v_exp_f32_e32 v31, v31
	v_exp_f32_e32 v32, v32
	v_exp_f32_e32 v33, v33
	v_exp_f32_e32 v22, v22
	v_exp_f32_e32 v23, v23
	v_exp_f32_e32 v24, v24
	v_exp_f32_e32 v25, v25
	v_pk_add_f32 v[30:31], v[30:31], s[50:51] op_sel_hi:[1,0]
	v_pk_add_f32 v[32:33], v[32:33], s[50:51] op_sel_hi:[1,0]
	v_pk_add_f32 v[22:23], v[22:23], s[50:51] op_sel_hi:[1,0]
	v_pk_add_f32 v[24:25], v[24:25], s[50:51] op_sel_hi:[1,0]
	v_rcp_f32_e32 v30, v30
	v_rcp_f32_e32 v31, v31
	v_rcp_f32_e32 v32, v32
	v_rcp_f32_e32 v33, v33
	v_rcp_f32_e32 v22, v22
	v_rcp_f32_e32 v23, v23
	v_rcp_f32_e32 v24, v24
	v_rcp_f32_e32 v25, v25
	v_pk_mul_f32 v[10:11], v[14:15], v[10:11]
	v_pk_mul_f32 v[12:13], v[16:17], v[12:13]
	v_pk_mul_f32 v[2:3], v[6:7], v[2:3]
	v_pk_mul_f32 v[4:5], v[8:9], v[4:5]
	v_pk_mul_f32 v[14:15], v[14:15], s[48:49] op_sel_hi:[1,0]
	v_pk_mul_f32 v[16:17], v[16:17], s[48:49] op_sel_hi:[1,0]
	v_pk_mul_f32 v[6:7], v[6:7], s[48:49] op_sel_hi:[1,0]
	v_pk_mul_f32 v[8:9], v[8:9], s[48:49] op_sel_hi:[1,0]
	v_pk_mul_f32 v[26:27], v[30:31], v[26:27]
	v_pk_mul_f32 v[28:29], v[32:33], v[28:29]
	v_pk_mul_f32 v[18:19], v[22:23], v[18:19]
	v_pk_mul_f32 v[20:21], v[24:25], v[20:21]
	v_cvt_pk_bf16_f32 v26, v26, v27
	v_cvt_pk_bf16_f32 v27, v28, v29
	v_cvt_pk_bf16_f32 v28, v18, v19
	v_cvt_pk_bf16_f32 v29, v20, v21
	v_add_u32_e32 v30, 0xa0, v148
	v_mad_i64_i32 v[30:31], s[14:15], v30, s7, v[140:141]
	v_lshl_add_u64 v[30:31], v[30:31], 0, v[142:143]
	global_store_dwordx4 v[30:31], v[26:29], off nt
	v_exp_f32_e32 v14, v14
	v_exp_f32_e32 v15, v15
	v_exp_f32_e32 v16, v16
	v_exp_f32_e32 v17, v17
	v_exp_f32_e32 v6, v6
	v_exp_f32_e32 v7, v7
	v_exp_f32_e32 v8, v8
	v_exp_f32_e32 v9, v9
	v_pk_add_f32 v[14:15], v[14:15], s[50:51] op_sel_hi:[1,0]
	v_pk_add_f32 v[16:17], v[16:17], s[50:51] op_sel_hi:[1,0]
	v_pk_add_f32 v[6:7], v[6:7], s[50:51] op_sel_hi:[1,0]
	v_pk_add_f32 v[8:9], v[8:9], s[50:51] op_sel_hi:[1,0]
	v_rcp_f32_e32 v14, v14
	v_rcp_f32_e32 v15, v15
	v_rcp_f32_e32 v16, v16
	v_rcp_f32_e32 v17, v17
	v_rcp_f32_e32 v6, v6
	v_rcp_f32_e32 v7, v7
	v_rcp_f32_e32 v8, v8
	v_rcp_f32_e32 v9, v9
	v_pk_mul_f32 v[10:11], v[14:15], v[10:11]
	v_pk_mul_f32 v[12:13], v[16:17], v[12:13]
	v_pk_mul_f32 v[2:3], v[6:7], v[2:3]
	v_pk_mul_f32 v[4:5], v[8:9], v[4:5]
	v_cvt_pk_bf16_f32 v10, v10, v11
	v_cvt_pk_bf16_f32 v11, v12, v13
	v_cvt_pk_bf16_f32 v12, v2, v3
	v_cvt_pk_bf16_f32 v13, v4, v5
	v_add_u32_e32 v14, 0xb0, v148
	v_mad_i64_i32 v[14:15], s[14:15], v14, s7, v[140:141]
	v_lshl_add_u64 v[14:15], v[14:15], 0, v[142:143]
	s_mov_b64 s[14:15], -1
	s_andn2_b64 vcc, exec, s[0:1]
	global_store_dwordx4 v[14:15], v[10:13], off nt
	s_cbranch_vccnz .LBB0_962
	s_andn2_b64 vcc, exec, s[2:3]
	s_cbranch_vccnz .LBB0_961
	s_barrier
	s_branch .LBB0_961
